# decode step's first state tile prefetched during the last pass-A unit (HBM read overlaps pass-A compute)
# speedup vs baseline: 1.0091x; 1.0091x over previous
; #define gate_w2 ((const float*)KPTR(8))
; #define gate_b ((const float*)KPTR(9))
; __global__ void __launch_bounds__(NTHR, 2) fwd_kernel(Args a) {
;     ...
;         for (int rp_ = 0; rp_ < REP_M1; ++rp_) {
;             PHASE_IDS
;             const float* w2 = gate_w2 + (size_t)l * RANK * QKD; const float* gb = gate_b + (size_t)l * QKD; const float* gn = gla_norm_g + (size_t)l * 1024;
;             for (int ra_ = 0; ra_ < REP_M1A; ++ra_) for (int u = bid; u < 512; u += G) gla_passA(lds, u, PR, GLRP, w2, gb, SUB, EB, QT, AM, tid, wid, lane);
.LBB0_346:
	s_or_b64 exec, exec, s[0:1]
	v_readlane_b32 s0, v244, 13
	v_readlane_b32 s1, v244, 14
	s_xor_b64 s[0:1], s[0:1], -1
	s_mov_b64 s[26:27], s[90:91]
	v_mov_b32_e32 v112, v210
	v_writelane_b32 v244, s0, 30
	s_waitcnt lgkmcnt(0)
	s_barrier
	s_load_dwordx4 s[28:31], s[26:27], 0x40
	s_load_dwordx2 s[2:3], s[26:27], 0x50
	v_writelane_b32 v244, s1, 31
	v_readfirstlane_b32 s6, v112
	v_readlane_b32 s0, v244, 32
	v_readlane_b32 s1, v244, 33
	s_lshl_b64 s[22:23], s[0:1], 11
	s_ashr_i32 s8, s6, 6
	s_waitcnt lgkmcnt(0)
	s_add_u32 s4, s28, s4
	s_addc_u32 s5, s29, s5
	s_movk_i32 s7, 0x100
	v_readlane_b32 s0, v245, 19
	s_add_u32 s38, s30, s22
	v_cmp_gt_i32_e64 s[40:41], s7, v112
	s_movk_i32 s7, 0x7f
	v_readlane_b32 s1, v245, 20
	v_and_b32_e32 v110, 63, v112
	s_addc_u32 s39, s31, s23
	v_lshlrev_b32_e32 v120, 2, v112
	v_cmp_lt_i32_e64 s[42:43], s7, v112
	v_ashrrev_i32_e32 v113, 31, v112
	s_and_b64 vcc, exec, s[0:1]
	s_cbranch_vccz .LBB0_357
; #define LAS __attribute__((address_space(3)))
; __device__ __forceinline__ void gla_passA(LAS unsigned char* lds, int uidx, const bf16_t* PR, const float* GLRP, const float* w2, const float* gb,
;                                           bf16_t* SUB, float* EB, bf16_t* QT, bf16_t* AM, int tid, int wid, int lane) {
;     const int b = uidx >> 7, c = (uidx >> 2) & 31, h = uidx & 3; const int tok0 = b * SEQ + c * 64; const int bh = b * 4 + h;
;     LAS float* Bc = (LAS float*)lds;
;     LAS float* bCs = Bc + 64 * 129;
;     LAS bf16_t* Qs = (LAS bf16_t*)(lds + 33536);
;     LAS bf16_t* Ks = Qs + 64 * 136;
;     LAS bf16_t* Kh = Ks + 64 * 136;
;     LAS bf16_t* Vn = Kh + 64 * 136;
;     const int r = lane & 15, q = lane >> 4;
;     const bf16_t* qp = PR + (size_t)(tok0 + (tid >> 3)) * PRW + 1024 + h * DK + (tid & 7) * 16;
;     const u32x4 qa = *(const u32x4*)qp, qb = *(const u32x4*)(qp + 8), ka = *(const u32x4*)(qp + 512), kb = *(const u32x4*)(qp + 520);
;     u32x4 vreg[4];
; #pragma unroll
;     for (int i = 0; i < 4; ++i) { const int id = tid + 512 * i; vreg[i] = *(const u32x4*)(PR + (size_t)(tok0 + (id >> 5)) * PRW + 2048 + h * DV + (id & 31) * 8); }
;     LAS float* Gs = (LAS float*)(lds + 120576);
;     LAS float* Tt = Gs + 64 * 16;
;     if (tid < 256) { const int t = tid >> 2, r4 = (tid & 3) * 4; const float* gp = GLRP + (size_t)(tok0 + t) * RANK + r4; f32x4 g = *(const f32x4*)gp;
; #pragma unroll
;         for (int sp = 1; sp < NSP1; ++sp) g += *(const f32x4*)(gp + (size_t)sp * MPAD * RANK);
;         *(LAS f32x4*)(Gs + t * 16 + r4) = g; }
;     const int kcol = tid & 127, tg = tid >> 7;
;     float wk[16];
; #pragma unroll
;     for (int rr = 0; rr < 16; ++rr) wk[rr] = w2[rr * QKD + h * DK + kcol];
;     const float bias = gb[h * DK + kcol];
; #pragma unroll
;     for (int i = 0; i < 4; ++i) { const int id = tid + 512 * i; *(LAS u32x4*)(Vn + (id >> 5) * 272 + (id & 31) * 8) = vreg[i]; }
	v_lshlrev_b32_e32 v0, 4, v112
	v_and_b32_e32 v0, 0x70, v0
	v_readlane_b32 s7, v245, 60
	v_lshlrev_b32_e32 v6, 2, v0
	v_ashrrev_i32_e32 v111, 3, v112
	v_lshl_add_u32 v122, v112, 2, s7
	v_add_u32_e32 v123, s7, v6
	v_readlane_b32 s7, v245, 61
	v_ashrrev_i32_e32 v4, 7, v112
	v_cmp_lt_i32_e64 s[44:45], 0, v4
	v_add_u32_e32 v124, s7, v6
	v_readlane_b32 s7, v245, 62
	v_cmp_lt_i32_e64 s[46:47], 1, v4
	v_cmp_lt_i32_e64 s[48:49], 2, v4
	v_add_u32_e32 v125, s7, v6
	v_readlane_b32 s7, v245, 63
	s_movk_i32 s23, 0x110
	s_lshl_b32 s22, s8, 5
	v_add_u32_e32 v126, s7, v6
	s_movk_i32 s7, 0x204
	v_mul_lo_u32 v4, v111, s7
	v_add3_u32 v127, 0, v4, v6
	v_mul_lo_u32 v4, v111, s23
	v_lshlrev_b32_e32 v6, 1, v0
	v_readlane_b32 s10, v244, 0
	v_and_b32_e32 v10, 15, v112
	s_and_b32 s7, s22, 32
	s_lshl_b32 s9, s8, 3
	v_add3_u32 v128, 0, v4, v6
	v_add3_u32 v129, s10, v4, v6
	v_bfi_b32 v11, -16, s9, v112
	v_or_b32_e32 v6, s7, v10
	s_or_b32 s9, s7, 16
	v_mul_u32_u24_e32 v13, 0x110, v6
	v_or_b32_e32 v6, s9, v10
	v_mul_u32_u24_e32 v15, 0x110, v6
	v_lshrrev_b32_e32 v6, 2, v110
	v_and_b32_e32 v6, 12, v6
	v_lshlrev_b32_e32 v1, 3, v112
	v_or_b32_e32 v8, s7, v6
	v_and_b32_e32 v2, 0xf8, v1
	v_add_u32_e32 v1, 0x200, v112
	v_or_b32_e32 v12, 2, v8
	v_ashrrev_i32_e32 v115, 5, v1
	v_add_u32_e32 v1, 0x400, v112
	v_cmp_gt_i32_e64 s[54:55], v12, v11
	v_or_b32_e32 v12, 3, v8
	v_ashrrev_i32_e32 v116, 5, v1
	v_add_u32_e32 v1, 0x600, v112
	v_ashrrev_i32_e32 v118, 2, v112
	v_lshlrev_b32_e32 v3, 2, v120
	v_cmp_gt_i32_e64 s[56:57], v12, v11
	v_or_b32_e32 v12, s9, v6
	v_ashrrev_i32_e32 v117, 5, v1
	v_lshlrev_b32_e32 v1, 6, v118
	v_and_b32_e32 v168, 48, v3
	v_readlane_b32 s0, v245, 58
	v_or_b32_e32 v14, 2, v12
	v_cmp_gt_i32_e64 s[62:63], v14, v11
	v_add3_u32 v119, s0, v1, v168
	v_readlane_b32 s0, v245, 59
	v_lshlrev_b32_e32 v14, 1, v10
	s_movk_i32 s1, 0x220
	v_and_b32_e32 v4, 48, v110
	v_cmp_gt_i32_e64 s[58:59], v12, v11
	v_cmp_lt_i32_e64 s[60:61], v12, v11
	v_or_b32_e32 v12, 3, v12
	v_add_u32_e32 v16, s0, v14
	v_add_u32_e32 v14, s10, v14
	s_and_b32 s10, s6, 0xffffffc0
	s_load_dwordx2 s[6:7], s[26:27], 0x98
	v_mul_lo_u32 v5, v115, s1
	v_add_u32_e32 v4, 0, v4
	v_cmp_gt_i32_e64 s[64:65], v12, v11
	v_lshrrev_b32_e32 v12, 1, v112
	v_mad_u64_u32 v[80:81], s[24:25], v11, s23, v[4:5]
	v_and_b32_e32 v12, 24, v12
	v_mad_u32_u24 v17, v12, s1, v16
	v_mad_u32_u24 v81, v12, s23, v14
	v_or_b32_e32 v12, 32, v12
	v_mad_u32_u24 v130, v12, s23, v14
	s_ashr_i32 s23, s22, 31
	s_waitcnt lgkmcnt(0)
	s_add_u32 s24, s6, 0x12900000
	s_addc_u32 s25, s7, 0
	s_add_u32 s28, s6, 0x1ad84000
	s_addc_u32 s29, s7, 0
	s_add_u32 s9, s6, 0x1ed84000
	v_lshlrev_b32_e32 v26, 6, v11
	s_addc_u32 s30, s7, 0
	v_ashrrev_i32_e32 v27, 31, v26
	s_add_u32 s34, s6, 0x1edc4000
	s_addc_u32 s35, s7, 0
	v_lshl_add_u64 v[28:29], s[6:7], 0, v[168:169]
	v_lshl_add_u64 v[26:27], v[26:27], 1, s[6:7]
	s_mov_b64 s[6:7], 0x1f5c4000
	v_ashrrev_i32_e32 v114, 5, v112
	v_cmp_gt_i32_e64 s[50:51], v8, v11
	v_cmp_lt_i32_e64 s[52:53], v8, v11
	v_lshlrev_b32_e32 v10, 8, v10
	v_lshl_add_u64 v[84:85], v[26:27], 0, s[6:7]
	v_lshrrev_b32_e32 v11, 4, v111
	s_movk_i32 s6, 0x2040
	v_and_b32_e32 v121, 0x7f, v112
	v_lshl_add_u32 v1, v2, 1, s0
	v_mul_lo_u32 v3, v114, s1
	v_mul_lo_u32 v7, v116, s1
	v_mul_lo_u32 v9, v117, s1
	v_mad_u32_u24 v19, v12, s1, v16
	v_or_b32_e32 v12, 0x1000, v10
	v_or_b32_e32 v14, 0x2000, v10
	v_or_b32_e32 v16, 0x3000, v10
	v_or_b32_e32 v18, 0x4000, v10
	v_or_b32_e32 v20, 0x5000, v10
	v_or_b32_e32 v22, 0x6000, v10
	v_or_b32_e32 v24, 0x7000, v10
	s_mov_b64 s[66:67], 0x212c4000
	v_mul_lo_u32 v21, v11, s6
	v_lshl_add_u64 v[82:83], v[28:29], 0, s[66:67]
	v_lshl_add_u32 v131, v121, 2, v21
	v_lshlrev_b32_e32 v132, 10, v11
	v_lshlrev_b32_e32 v86, 1, v2
	v_add_u32_e32 v133, v1, v3
	v_add_u32_e32 v134, v1, v5
	v_add_u32_e32 v135, v1, v7
	v_add_u32_e32 v136, v1, v9
	v_lshlrev_b32_e32 v168, 1, v0
	v_add_u32_e32 v137, v4, v13
	v_add_u32_e32 v138, v4, v15
	v_lshlrev_b32_e32 v88, 1, v8
	v_add_u32_e32 v139, s10, v17
	v_add_u32_e32 v140, s10, v19
	v_lshlrev_b32_e32 v90, 1, v6
	v_lshlrev_b32_e32 v92, 1, v10
	v_lshlrev_b32_e32 v94, 1, v12
	v_lshlrev_b32_e32 v96, 1, v14
	v_lshlrev_b32_e32 v98, 1, v16
	v_lshlrev_b32_e32 v100, 1, v18
	v_lshlrev_b32_e32 v102, 1, v20
	v_lshlrev_b32_e32 v104, 1, v22
	v_lshlrev_b32_e32 v106, 1, v24
	v_readlane_b32 s66, v245, 52
	v_readlane_b32 s67, v245, 53
	v_lshrrev_b32_e32 v247, 3, v112
	v_and_b32_e32 v248, 7, v112
	v_lshlrev_b32_e32 v247, 13, v247
	v_lshl_or_b32 v247, v248, 5, v247
	v_lshrrev_b32_e32 v248, 5, v112
	v_and_b32_e32 v249, 31, v112
	v_lshlrev_b32_e32 v248, 13, v248
	v_lshl_or_b32 v248, v249, 4, v248
	v_and_b32_e32 v249, 0xff, v112
	v_lshlrev_b32_e32 v249, 4, v249
	s_mov_b32 s72, -1
	s_mov_b32 s79, 0
	s_mov_b32 s98, s66
	s_ashr_i32 s99, s98, 7
	s_lshl_b32 s99, s99, 11
	s_bfe_u32 s100, s98, 0x50002
	s_lshl_b32 s100, s100, 6
	s_or_b32 s99, s99, s100
	s_and_b32 s98, s98, 3
	s_lshl_b32 s73, s98, 8
	s_lshl_b32 s100, s99, 13
	s_add_u32 s100, s100, s73
	s_add_u32 s100, s24, s100
	s_addc_u32 s101, s25, 0
	global_load_dwordx4 v[178:181], v247, s[100:101] offset:2048
	global_load_dwordx4 v[182:185], v247, s[100:101] offset:2064
	global_load_dwordx4 v[186:189], v247, s[100:101] offset:3072
	global_load_dwordx4 v[190:193], v247, s[100:101] offset:3088
	s_add_u32 s73, s73, 0x1000
	s_add_u32 s100, s100, s73
	s_addc_u32 s101, s101, 0
	global_load_dwordx4 v[194:197], v248, s[100:101]
	s_add_u32 s100, s100, 0x20000
	s_addc_u32 s101, s101, 0
	global_load_dwordx4 v[198:201], v248, s[100:101]
	s_add_u32 s100, s100, 0x20000
	s_addc_u32 s101, s101, 0
	global_load_dwordx4 v[202:205], v248, s[100:101]
	s_add_u32 s100, s100, 0x20000
	s_addc_u32 s101, s101, 0
	global_load_dwordx4 v[206:209], v248, s[100:101]
	s_lshl_b32 s99, s99, 6
	s_add_u32 s100, s24, 0x0e9c4000
	s_addc_u32 s101, s25, 0
	s_add_u32 s100, s100, s99
	s_addc_u32 s101, s101, 0
	global_load_dwordx4 v[142:145], v249, s[100:101]
	s_add_u32 s100, s100, 0x84000
	s_addc_u32 s101, s101, 0
	global_load_dwordx4 v[146:149], v249, s[100:101]
	s_add_u32 s100, s100, 0x84000
	s_addc_u32 s101, s101, 0
	global_load_dwordx4 v[150:153], v249, s[100:101]
	s_add_u32 s100, s100, 0x84000
	s_addc_u32 s101, s101, 0
	global_load_dwordx4 v[154:157], v249, s[100:101]
	s_waitcnt vmcnt(0)
	s_branch .LBB0_349

; #define LAS __attribute__((address_space(3)))
; __device__ __forceinline__ void gla_passA(LAS unsigned char* lds, int uidx, const bf16_t* PR, const float* GLRP, const float* w2, const float* gb,
;                                           bf16_t* SUB, float* EB, bf16_t* QT, bf16_t* AM, int tid, int wid, int lane) {
;     ...
;     LAS float* Tt = Gs + 64 * 16;
;     if (tid < 256) { const int t = tid >> 2, r4 = (tid & 3) * 4; const float* gp = GLRP + (size_t)(tok0 + t) * RANK + r4; f32x4 g = *(const f32x4*)gp;
; #pragma unroll
;         for (int sp = 1; sp < NSP1; ++sp) g += *(const f32x4*)(gp + (size_t)sp * MPAD * RANK);
;         *(LAS f32x4*)(Gs + t * 16 + r4) = g; }
;     const int kcol = tid & 127, tg = tid >> 7;
;     float wk[16];
; #pragma unroll
;     for (int rr = 0; rr < 16; ++rr) wk[rr] = w2[rr * QKD + h * DK + kcol];
;     const float bias = gb[h * DK + kcol];
; #pragma unroll
;     for (int i = 0; i < 4; ++i) { const int id = tid + 512 * i; *(LAS u32x4*)(Vn + (id >> 5) * 272 + (id & 31) * 8) = vreg[i]; }
;     __syncthreads();
.Lpa_w2ok:
	v_mov_b32_e32 v34, v228
	v_mov_b32_e32 v35, v229
	v_mov_b32_e32 v36, v230
	v_mov_b32_e32 v37, v231
	v_mov_b32_e32 v38, v232
	v_mov_b32_e32 v39, v233
	v_mov_b32_e32 v40, v234
	v_mov_b32_e32 v41, v235
	v_mov_b32_e32 v42, v236
	v_mov_b32_e32 v43, v237
	v_mov_b32_e32 v44, v238
	v_mov_b32_e32 v45, v239
	v_mov_b32_e32 v46, v240
	v_mov_b32_e32 v47, v241
	v_mov_b32_e32 v48, v242
	v_mov_b32_e32 v49, v243
	v_mov_b32_e32 v50, v158
	ds_write_b128 v133, v[194:197]
	ds_write_b128 v134, v[198:201]
	ds_write_b128 v135, v[202:205]
	ds_write_b128 v136, v[206:209]
	v_mov_b32_e32 v16, 0
	s_mov_b32 s7, 16
	v_mov_b32_e32 v17, v132
	v_mov_b32_e32 v18, v131
	s_waitcnt lgkmcnt(0)
	s_barrier
	s_add_i32 s98, s66, s82
	s_cmpk_gt_i32 s98, 0x1ff
	s_cbranch_scc1 .Lpa_gpf
	s_ashr_i32 s99, s98, 7
	s_lshl_b32 s99, s99, 11
	s_bfe_u32 s100, s98, 0x50002
	s_lshl_b32 s100, s100, 6
	s_or_b32 s99, s99, s100
	s_and_b32 s98, s98, 3
	s_lshl_b32 s73, s98, 8
	s_lshl_b32 s100, s99, 13
	s_add_u32 s100, s100, s73
	s_add_u32 s100, s24, s100
	s_addc_u32 s101, s25, 0
	global_load_dwordx4 v[178:181], v247, s[100:101] offset:2048
	global_load_dwordx4 v[182:185], v247, s[100:101] offset:2064
	global_load_dwordx4 v[186:189], v247, s[100:101] offset:3072
	global_load_dwordx4 v[190:193], v247, s[100:101] offset:3088
	s_add_u32 s73, s73, 0x1000
	s_add_u32 s100, s100, s73
	s_addc_u32 s101, s101, 0
	global_load_dwordx4 v[194:197], v248, s[100:101]
	s_add_u32 s100, s100, 0x20000
	s_addc_u32 s101, s101, 0
	global_load_dwordx4 v[198:201], v248, s[100:101]
	s_add_u32 s100, s100, 0x20000
	s_addc_u32 s101, s101, 0
	global_load_dwordx4 v[202:205], v248, s[100:101]
	s_add_u32 s100, s100, 0x20000
	s_addc_u32 s101, s101, 0
	global_load_dwordx4 v[206:209], v248, s[100:101]
	s_lshl_b32 s99, s99, 6
	s_add_u32 s100, s24, 0x0e9c4000
	s_addc_u32 s101, s25, 0
	s_add_u32 s100, s100, s99
	s_addc_u32 s101, s101, 0
	global_load_dwordx4 v[142:145], v249, s[100:101]
	s_add_u32 s100, s100, 0x84000
	s_addc_u32 s101, s101, 0
	global_load_dwordx4 v[146:149], v249, s[100:101]
	s_add_u32 s100, s100, 0x84000
	s_addc_u32 s101, s101, 0
	global_load_dwordx4 v[150:153], v249, s[100:101]
	s_add_u32 s100, s100, 0x84000
	s_addc_u32 s101, s101, 0
	global_load_dwordx4 v[154:157], v249, s[100:101]
	s_branch .Lpa_nopf
.Lpa_gpf:
	s_load_dwordx2 s[100:101], s[90:91], 0x18
	v_readlane_b32 s98, v245, 50
	v_readlane_b32 s99, v245, 51
	v_readlane_b32 s73, v244, 32
	v_and_b32_e32 v250, 63, v112
	v_lshlrev_b32_e32 v250, 4, v250
	s_lshl_b32 s77, s8, 14
	s_lshl_b32 s73, s73, 26
	s_waitcnt lgkmcnt(0)
	s_add_u32 s100, s100, s98
	s_addc_u32 s101, s101, s99
	s_add_u32 s100, s100, s77
	s_addc_u32 s101, s101, 0
	s_add_u32 s100, s100, s73
	s_addc_u32 s101, s101, 0
	global_load_dwordx4 v[142:145], v250, s[100:101] nt
	global_load_dwordx4 v[146:149], v250, s[100:101] offset:1024 nt
	global_load_dwordx4 v[150:153], v250, s[100:101] offset:2048 nt
	global_load_dwordx4 v[154:157], v250, s[100:101] offset:3072 nt
	s_add_u32 s100, s100, 0x1000
	s_addc_u32 s101, s101, 0
	global_load_dwordx4 v[178:181], v250, s[100:101] nt
	global_load_dwordx4 v[182:185], v250, s[100:101] offset:1024 nt
	global_load_dwordx4 v[186:189], v250, s[100:101] offset:2048 nt
	global_load_dwordx4 v[190:193], v250, s[100:101] offset:3072 nt
	s_add_u32 s100, s100, 0x1000
	s_addc_u32 s101, s101, 0
	global_load_dwordx4 v[194:197], v250, s[100:101] nt
	global_load_dwordx4 v[198:201], v250, s[100:101] offset:1024 nt
	global_load_dwordx4 v[202:205], v250, s[100:101] offset:2048 nt
	global_load_dwordx4 v[206:209], v250, s[100:101] offset:3072 nt
	s_add_u32 s100, s100, 0x1000
	s_addc_u32 s101, s101, 0
	global_load_dwordx4 v[228:231], v250, s[100:101] nt
	global_load_dwordx4 v[232:235], v250, s[100:101] offset:1024 nt
	global_load_dwordx4 v[236:239], v250, s[100:101] offset:2048 nt
	global_load_dwordx4 v[240:243], v250, s[100:101] offset:3072 nt
	s_mov_b32 s79, 1

; template <bool WITH_O> __device__ __forceinline__ void gla_sample(LAS unsigned char* lds, int uidx, const float* PRS, const float* GLRP, const float* w2, const float* gb, const float* gn, ...
;     ...
;     const size_t sb = ((size_t)(s * 4 + h) * DK) * DV + (tid & 63) * 4; f32x4 S[16];
; #pragma unroll
;     for (int kk = 0; kk < 16; ++kk) S[kk] = __builtin_nontemporal_load((const f32x4*)(s_in + sb + (size_t)(16 * wid + kk) * DV));
;     ...
;     const int dv4 = (tid & 63) * 4; const f32x4 v = prs_sum4(PRS, s, 4096 + h * DV + dv4);
.LBB0_360:
	s_cmp_eq_u32 s79, 0
	s_cbranch_scc1 .Lgs_small
	v_mov_b32_e32 v60, v142
	v_mov_b32_e32 v61, v143
	v_mov_b32_e32 v62, v144
	v_mov_b32_e32 v63, v145
	v_mov_b32_e32 v56, v146
	v_mov_b32_e32 v57, v147
	v_mov_b32_e32 v58, v148
	v_mov_b32_e32 v59, v149
	v_mov_b32_e32 v52, v150
	v_mov_b32_e32 v53, v151
	v_mov_b32_e32 v54, v152
	v_mov_b32_e32 v55, v153
	v_mov_b32_e32 v48, v154
	v_mov_b32_e32 v49, v155
	v_mov_b32_e32 v50, v156
	v_mov_b32_e32 v51, v157
	v_mov_b32_e32 v44, v178
	v_mov_b32_e32 v45, v179
	v_mov_b32_e32 v46, v180
	v_mov_b32_e32 v47, v181
	v_mov_b32_e32 v40, v182
	v_mov_b32_e32 v41, v183
	v_mov_b32_e32 v42, v184
	v_mov_b32_e32 v43, v185
	v_mov_b32_e32 v36, v186
	v_mov_b32_e32 v37, v187
	v_mov_b32_e32 v38, v188
	v_mov_b32_e32 v39, v189
	v_mov_b32_e32 v32, v190
	v_mov_b32_e32 v33, v191
	v_mov_b32_e32 v34, v192
	v_mov_b32_e32 v35, v193
	v_mov_b32_e32 v28, v194
	v_mov_b32_e32 v29, v195
	v_mov_b32_e32 v30, v196
	v_mov_b32_e32 v31, v197
	v_mov_b32_e32 v24, v198
	v_mov_b32_e32 v25, v199
	v_mov_b32_e32 v26, v200
	v_mov_b32_e32 v27, v201
	v_mov_b32_e32 v20, v202
	v_mov_b32_e32 v21, v203
	v_mov_b32_e32 v22, v204
	v_mov_b32_e32 v23, v205
	v_mov_b32_e32 v16, v206
	v_mov_b32_e32 v17, v207
	v_mov_b32_e32 v18, v208
	v_mov_b32_e32 v19, v209
	v_mov_b32_e32 v12, v228
	v_mov_b32_e32 v13, v229
	v_mov_b32_e32 v14, v230
	v_mov_b32_e32 v15, v231
	v_mov_b32_e32 v8, v232
	v_mov_b32_e32 v9, v233
	v_mov_b32_e32 v10, v234
	v_mov_b32_e32 v11, v235
	v_mov_b32_e32 v4, v236
	v_mov_b32_e32 v5, v237
	v_mov_b32_e32 v6, v238
	v_mov_b32_e32 v7, v239
	v_mov_b32_e32 v0, v240
	v_mov_b32_e32 v1, v241
	v_mov_b32_e32 v2, v242
	v_mov_b32_e32 v3, v243
.Lgs_small:
	s_ashr_i32 s100, s55, 2
	s_mul_i32 s100, s100, 0x6400
	s_and_b32 s101, s55, 3
	s_lshl_b32 s101, s101, 10
	s_add_u32 s100, s100, s101
	s_add_u32 s98, s22, s100
	s_addc_u32 s99, s23, 0
	v_lshlrev_b32_e32 v196, 2, v121
	v_add_u32_e32 v196, 0x4000, v196
	v_and_b32_e32 v197, 0xff, v112
	v_lshlrev_b32_e32 v197, 2, v197
	v_add_u32_e32 v198, 0x5000, v197
	global_load_dwordx4 v[180:183], v196, s[98:99]
	global_load_dword v200, v198, s[98:99]
	s_add_u32 s100, s98, 0x320000
	s_addc_u32 s101, s99, 0
	global_load_dwordx4 v[184:187], v196, s[100:101]
	global_load_dword v201, v198, s[100:101]
	s_add_u32 s100, s98, 0x640000
	s_addc_u32 s101, s99, 0
	global_load_dwordx4 v[188:191], v196, s[100:101]
	global_load_dword v202, v198, s[100:101]
	s_add_u32 s100, s98, 0x960000
	s_addc_u32 s101, s99, 0
	global_load_dwordx4 v[192:195], v196, s[100:101]
	global_load_dword v203, v198, s[100:101]
	s_and_b32 s100, s55, 3
	s_lshl_b32 s100, s100, 10
	s_add_u32 s100, s2, s100
	s_addc_u32 s101, s3, 0
	global_load_dword v204, v197, s[100:101]
	s_ashr_i32 s8, s55, 2
	s_cmp_eq_u32 s79, 0
	s_mov_b32 s79, 0
	s_cbranch_scc0 .Lgs_loaded
	v_lshl_add_u64 v[0:1], s[24:25], 0, v[114:115]
	v_add_co_u32_e32 v2, vcc, 0x1000, v0
	global_load_dwordx4 v[60:63], v[0:1], off nt
	global_load_dwordx4 v[56:59], v[0:1], off offset:1024 nt
	global_load_dwordx4 v[52:55], v[0:1], off offset:2048 nt
	global_load_dwordx4 v[48:51], v[0:1], off offset:3072 nt
	v_addc_co_u32_e32 v3, vcc, 0, v1, vcc
	global_load_dwordx4 v[44:47], v[2:3], off nt
	global_load_dwordx4 v[40:43], v[2:3], off offset:1024 nt
	global_load_dwordx4 v[36:39], v[2:3], off offset:2048 nt
	global_load_dwordx4 v[32:35], v[2:3], off offset:3072 nt
	v_add_co_u32_e32 v2, vcc, s59, v0
	s_ashr_i32 s8, s55, 2
	s_nop 0
	v_addc_co_u32_e32 v3, vcc, 0, v1, vcc
	v_add_co_u32_e32 v0, vcc, 0x3000, v0
	global_load_dwordx4 v[28:31], v[2:3], off nt
	global_load_dwordx4 v[24:27], v[2:3], off offset:1024 nt
	global_load_dwordx4 v[20:23], v[2:3], off offset:2048 nt
	global_load_dwordx4 v[16:19], v[2:3], off offset:3072 nt
	v_addc_co_u32_e32 v1, vcc, 0, v1, vcc
	global_load_dwordx4 v[12:15], v[0:1], off nt
	global_load_dwordx4 v[8:11], v[0:1], off offset:1024 nt
	global_load_dwordx4 v[4:7], v[0:1], off offset:2048 nt
	s_nop 0
	global_load_dwordx4 v[0:3], v[0:1], off offset:3072 nt
; __device__ __forceinline__ float logsig_f(float z) { return fminf(z, 0.f) - __logf(1.f + __expf(-fabsf(z))); }
; template <bool WITH_O> __device__ __forceinline__ void gla_sample(LAS unsigned char* lds, int uidx, const float* PRS, const float* GLRP, const float* w2, const float* gb, const float* gn, ...
;     ...
;     if (tid < DK) { const int col = h * DK + tid; float z = gb[col];
; #pragma unroll
;         for (int rr = 0; rr < RANK; ++rr) { float g = 0.f;
; #pragma unroll
;             for (int sp = 0; sp < NSP1; ++sp) g += GLRP[((size_t)sp * MPAD + row) * RANK + rr];
;             z += g * w2[rr * QKD + col]; }
;         smA[tid] = __expf(logsig_f(z) * (1.f / 16.f)); smK[tid] = prs_sum(PRS, s, 3584 + col); if (WITH_O) smQ[tid] = prs_sum(PRS, s, 3072 + col) * 0.08838834764831845f; }
.Lgs_loaded:
	s_mul_hi_i32 s49, s8, 0x6400
	s_mul_i32 s48, s8, 0x6400
	s_and_saveexec_b64 s[6:7], s[42:43]
	s_xor_b64 s[6:7], exec, s[6:7]
	s_or_saveexec_b64 s[52:53], s[6:7]
	s_and_b32 s6, s55, 3
	s_add_i32 s34, s8, 0x2000
	v_mov_b64_e32 v[72:73], s[48:49]
	s_xor_b64 exec, exec, s[52:53]
	s_cbranch_execz .LBB0_362
	s_ashr_i32 s35, s34, 31
	v_lshl_add_u32 v64, s6, 7, v112
	s_lshl_b64 s[46:47], s[34:35], 6
	v_lshlrev_b32_e32 v64, 2, v64
	s_add_u32 s46, s30, s46
	s_addc_u32 s47, s31, s47
	global_load_dword v65, v64, s[38:39]
	global_load_dwordx4 v[66:69], v169, s[46:47]
	global_load_dwordx4 v[74:77], v169, s[46:47] offset:16
	global_load_dwordx4 v[78:81], v169, s[46:47] offset:32
	global_load_dwordx4 v[82:85], v169, s[46:47] offset:48
	s_add_u32 s56, s46, 0x84000
	s_addc_u32 s57, s47, 0
	global_load_dwordx4 v[86:89], v169, s[56:57]
	global_load_dwordx4 v[90:93], v169, s[56:57] offset:16
	global_load_dwordx4 v[94:97], v169, s[56:57] offset:32
	global_load_dwordx4 v[98:101], v169, s[56:57] offset:48
	s_add_u32 s56, s46, 0x108000
	s_addc_u32 s57, s47, 0
	global_load_dwordx4 v[102:105], v169, s[56:57]
	global_load_dwordx4 v[106:109], v169, s[56:57] offset:16
	global_load_dwordx4 v[116:119], v169, s[56:57] offset:32
	global_load_dwordx4 v[126:129], v169, s[56:57] offset:48
	s_add_u32 s56, s46, 0x18c000
	s_addc_u32 s57, s47, 0
	global_load_dwordx4 v[130:133], v169, s[56:57]
	global_load_dwordx4 v[134:137], v169, s[56:57] offset:16
	global_load_dwordx4 v[138:141], v169, s[56:57] offset:32
	global_load_dwordx4 v[142:145], v169, s[56:57] offset:48
	global_load_dword v70, v64, s[4:5]
	global_load_dword v71, v64, s[4:5] offset:2048
	s_add_u32 s56, s4, 0x1000
	s_addc_u32 s57, s5, 0
	global_load_dword v110, v64, s[56:57]
	global_load_dword v111, v64, s[56:57] offset:2048
	s_add_u32 s56, s4, 0x2000
	s_addc_u32 s57, s5, 0
	global_load_dword v125, v64, s[56:57]
	global_load_dword v146, v64, s[56:57] offset:2048
	s_add_u32 s56, s4, 0x3000
	s_addc_u32 s57, s5, 0
	global_load_dword v147, v64, s[56:57]
	global_load_dword v148, v64, s[56:57] offset:2048
	s_add_u32 s56, s4, 0x4000
	s_addc_u32 s57, s5, 0
	global_load_dword v149, v64, s[56:57]
	global_load_dword v150, v64, s[56:57] offset:2048
	s_add_u32 s56, s4, 0x5000
	s_addc_u32 s57, s5, 0
	global_load_dword v151, v64, s[56:57]
	global_load_dword v152, v64, s[56:57] offset:2048
	s_add_u32 s56, s4, 0x6000
	s_addc_u32 s57, s5, 0
	global_load_dword v153, v64, s[56:57]
	global_load_dword v154, v64, s[56:57] offset:2048
	s_add_u32 s56, s4, 0x7000
	s_addc_u32 s57, s5, 0
	global_load_dword v155, v64, s[56:57]
	global_load_dword v156, v64, s[56:57] offset:2048
	s_mul_i32 s98, s8, 0x6400
	s_add_u32 s98, s22, s98
	s_addc_u32 s99, s23, 0
	s_add_u32 s98, s98, 0x3000
	s_addc_u32 s99, s99, 0
	global_load_dword v157, v64, s[98:99] offset:2048
	global_load_dword v161, v64, s[98:99]
	s_add_u32 s56, s98, 0x320000
	s_addc_u32 s57, s99, 0
	global_load_dword v158, v64, s[56:57] offset:2048
	global_load_dword v162, v64, s[56:57]
	s_add_u32 s56, s98, 0x640000
	s_addc_u32 s57, s99, 0
	global_load_dword v159, v64, s[56:57] offset:2048
	global_load_dword v163, v64, s[56:57]
	s_add_u32 s56, s98, 0x960000
	s_addc_u32 s57, s99, 0
	global_load_dword v160, v64, s[56:57] offset:2048
	global_load_dword v164, v64, s[56:57]
	s_waitcnt vmcnt(0)
	v_add_f32_e32 v165, 0, v66
	v_add_f32_e32 v165, v165, v86
	v_add_f32_e32 v165, v165, v102
	v_add_f32_e32 v165, v165, v130
	v_fmac_f32_e32 v65, v165, v70
	v_add_f32_e32 v165, 0, v67
	v_add_f32_e32 v165, v165, v87
	v_add_f32_e32 v165, v165, v103
	v_add_f32_e32 v165, v165, v131
	v_fmac_f32_e32 v65, v165, v71
	v_add_f32_e32 v165, 0, v68
	v_add_f32_e32 v165, v165, v88
	v_add_f32_e32 v165, v165, v104
	v_add_f32_e32 v165, v165, v132
	v_fmac_f32_e32 v65, v165, v110
	v_add_f32_e32 v165, 0, v69
	v_add_f32_e32 v165, v165, v89
	v_add_f32_e32 v165, v165, v105
	v_add_f32_e32 v165, v165, v133
	v_fmac_f32_e32 v65, v165, v111
	v_add_f32_e32 v165, 0, v74
	v_add_f32_e32 v165, v165, v90
	v_add_f32_e32 v165, v165, v106
	v_add_f32_e32 v165, v165, v134
	v_fmac_f32_e32 v65, v165, v125
	v_add_f32_e32 v165, 0, v75
	v_add_f32_e32 v165, v165, v91
	v_add_f32_e32 v165, v165, v107
	v_add_f32_e32 v165, v165, v135
	v_fmac_f32_e32 v65, v165, v146
	v_add_f32_e32 v165, 0, v76
	v_add_f32_e32 v165, v165, v92
	v_add_f32_e32 v165, v165, v108
	v_add_f32_e32 v165, v165, v136
	v_fmac_f32_e32 v65, v165, v147
	v_add_f32_e32 v165, 0, v77
	v_add_f32_e32 v165, v165, v93
	v_add_f32_e32 v165, v165, v109
	v_add_f32_e32 v165, v165, v137
	v_fmac_f32_e32 v65, v165, v148
	v_add_f32_e32 v165, 0, v78
	v_add_f32_e32 v165, v165, v94
	v_add_f32_e32 v165, v165, v116
	v_add_f32_e32 v165, v165, v138
	v_fmac_f32_e32 v65, v165, v149
	v_add_f32_e32 v165, 0, v79
	v_add_f32_e32 v165, v165, v95
	v_add_f32_e32 v165, v165, v117
	v_add_f32_e32 v165, v165, v139
	v_fmac_f32_e32 v65, v165, v150
	v_add_f32_e32 v165, 0, v80
	v_add_f32_e32 v165, v165, v96
	v_add_f32_e32 v165, v165, v118
	v_add_f32_e32 v165, v165, v140
	v_fmac_f32_e32 v65, v165, v151
	v_add_f32_e32 v165, 0, v81
	v_add_f32_e32 v165, v165, v97
	v_add_f32_e32 v165, v165, v119
	v_add_f32_e32 v165, v165, v141
	v_fmac_f32_e32 v65, v165, v152
	v_add_f32_e32 v165, 0, v82
	v_add_f32_e32 v165, v165, v98
	v_add_f32_e32 v165, v165, v126
	v_add_f32_e32 v165, v165, v142
	v_fmac_f32_e32 v65, v165, v153
	v_add_f32_e32 v165, 0, v83
	v_add_f32_e32 v165, v165, v99
	v_add_f32_e32 v165, v165, v127
	v_add_f32_e32 v165, v165, v143
	v_fmac_f32_e32 v65, v165, v154
	v_add_f32_e32 v165, 0, v84
	v_add_f32_e32 v165, v165, v100
	v_add_f32_e32 v165, v165, v128
	v_add_f32_e32 v165, v165, v144
	v_fmac_f32_e32 v65, v165, v155
	v_add_f32_e32 v165, 0, v85
	v_add_f32_e32 v165, v165, v101
	v_add_f32_e32 v165, v165, v129
	v_add_f32_e32 v165, v165, v145
	v_fmac_f32_e32 v65, v165, v156
	v_mul_f32_e64 v166, |v65|, s17
	v_exp_f32_e32 v166, v166
	v_min_f32_e32 v167, 0, v65
	v_add_f32_e32 v166, 1.0, v166
	v_cmp_gt_f32_e32 vcc, s14, v166
	s_nop 1
	v_cndmask_b32_e64 v168, 0, 32, vcc
	v_ldexp_f32 v166, v166, v168
	v_log_f32_e32 v166, v166
	s_nop 0
	v_mul_f32_e32 v168, 0x3f317217, v166
	v_fma_f32 v168, v166, s18, -v168
	v_fmac_f32_e32 v168, 0x3377d1cf, v166
	v_fmac_f32_e32 v168, 0x3f317217, v166
	v_cmp_lt_f32_e64 s[46:47], |v166|, s19
	s_nop 1
	v_cndmask_b32_e64 v166, v166, v168, s[46:47]
	v_cndmask_b32_e32 v168, 0, v218, vcc
	v_sub_f32_e32 v166, v166, v168
	v_sub_f32_e32 v167, v167, v166
	v_mul_f32_e32 v167, 0x3d800000, v167
	v_mul_f32_e32 v167, 0x3fb8aa3b, v167
	v_exp_f32_e32 v178, v167
	v_add_f32_e32 v166, 0, v157
	v_add_f32_e32 v166, v166, v158
	v_add_f32_e32 v166, v166, v159
	v_add_f32_e32 v166, v166, v160
	v_add_f32_e32 v167, 0, v161
	v_add_f32_e32 v167, v167, v162
	v_add_f32_e32 v167, v167, v163
	v_add_f32_e32 v167, v167, v164
	v_mul_f32_e32 v167, 0x3db504f3, v167
	ds_write2st64_b32 v122, v178, v166 offset1:2
	ds_write_b32 v122, v167 offset:1024
